# static s_setprio 1 for waves 4-7 (younger half) during retention+attention, otherwise same as best
# baseline (speedup 1.0000x reference)
; DI void grid_barrier(unsigned* bar, unsigned& nbar, const bool hier, const unsigned xcd, const unsigned per_xcd) {
;     ...
;     __syncthreads();
;     ++nbar;
; __global__ void __launch_bounds__(512, 2) mega(Params p) {
;     ...
;         if (3 > p.ph_lo) grid_barrier(bar, nbar, hier, my_xcd, (unsigned)G / 8u);
;     ...
;             phase_retention(p, lds, c_eff); __syncthreads();
;     ...
;             phase_attention(p, lds);
.LBB0_198:
	s_or_b64 exec, exec, s[0:1]
	s_barrier
	v_readfirstlane_b32 s98, v0
	s_nop 3
	s_and_b32 s98, s98, 0x3ff
	s_lshr_b32 s98, s98, 6
	s_cmp_ge_u32 s98, 4
	s_cbranch_scc0 .Lprio_skip_ret
	s_setprio 1
.Lprio_skip_ret:
	s_cmpk_lt_i32 s81, 0x100
	v_lshrrev_b32_e32 v140, 4, v74
	s_cbranch_scc0 .LBB0_178

; DI void grid_barrier(unsigned* bar, unsigned& nbar, const bool hier, const unsigned xcd, const unsigned per_xcd) {
;     asm volatile("s_waitcnt vmcnt(0)" ::: "memory");
;     __syncthreads();
;     if (threadIdx.x == 0) {
;         __builtin_amdgcn_fence(__ATOMIC_RELEASE, "agent");
;         asm volatile("s_waitcnt vmcnt(0)" ::: "memory");
;         const unsigned gen = nbar + 1u;
;         if (hier) {
;             unsigned* xc = bar + 256 + 64 * xcd; unsigned* top = bar + 1024;
;             const unsigned old = __hip_atomic_fetch_add(xc, 1u, __ATOMIC_RELAXED, __HIP_MEMORY_SCOPE_AGENT);
;             if (old + 1u == gen * per_xcd) __hip_atomic_fetch_add(top, 1u, __ATOMIC_RELAXED, __HIP_MEMORY_SCOPE_AGENT);
;             while (__hip_atomic_load(top, __ATOMIC_RELAXED, __HIP_MEMORY_SCOPE_AGENT) < gen * 8u) __builtin_amdgcn_s_sleep(1);
;         } else {
;             const unsigned target = gen * gridDim.x;
;             __hip_atomic_fetch_add(bar, 1u, __ATOMIC_RELAXED, __HIP_MEMORY_SCOPE_AGENT);
;             while (__hip_atomic_load(bar, __ATOMIC_RELAXED, __HIP_MEMORY_SCOPE_AGENT) < target) __builtin_amdgcn_s_sleep(1);
;         }
;         __builtin_amdgcn_fence(__ATOMIC_ACQUIRE, "agent");
;         asm volatile("s_waitcnt vmcnt(0)" ::: "memory");
;     }
;     __syncthreads();
;     ++nbar;
; }
; __global__ void __launch_bounds__(512, 2) mega(Params p) {
;     ...
;         if (4 > p.ph_lo) grid_barrier(bar, nbar, hier, my_xcd, (unsigned)G / 8u);
.LBB0_263:
	s_or_b64 exec, exec, s[0:1]
	s_barrier
	s_setprio 0
